# attention softmax row-max reduction across lane groups with v_permlane16_swap / v_permlane32_swap instead of two ds_bpermute round trips
# speedup vs baseline: 1.0031x; 1.0031x over previous
; #define LAS __attribute__((address_space(3)))
; __device__ __forceinline__ unsigned cvt_pk_bf16(float lo, float hi) { const f32x2_t v = {lo, hi}; const bf16x2_t b = __builtin_convertvector(v, bf16x2_t); return __builtin_bit_cast(unsigned, b); }
; __device__ void attn_phase(unsigned char* smem, const Params& p, int chunk) {
;     ...
;         float mx = -1e30f;
; #pragma unroll
;         for (int kt = 0; kt < 9; ++kt)
; #pragma unroll
;             for (int i = 0; i < 4; ++i) { const bool valid = (ub + (unsigned)(16 * kt + i)) <= rng;
;                 const float v = valid ? __builtin_fmaf(s[kt][i], 0.125f * 1.4426950408889634f, bl[16 * kt + i]) : -1e30f; s[kt][i] = v; mx = fmaxf(mx, v); }
;         mx = fmaxf(mx, __shfl_xor(mx, 16)); mx = fmaxf(mx, __shfl_xor(mx, 32));
;         float den = 0.f;
; #pragma unroll
;         for (int kt = 0; kt < 9; ++kt)
; #pragma unroll
;             for (int i = 0; i < 4; ++i) { const float e = __builtin_amdgcn_exp2f(s[kt][i] - mx); s[kt][i] = e; den += e; }
;         den += __shfl_xor(den, 16); den += __shfl_xor(den, 32);
;         f32x4 o[4];
; #pragma unroll
;         for (int et = 0; et < 4; ++et) o[et] = (f32x4){0.f, 0.f, 0.f, 0.f};
;         const bf16_t* vbase = Vs + (hoff + qs * 16 + 4 * g4 + (r16 >> 2)) * VSR + 4 * (r16 & 3);
; #pragma unroll
;         for (int cc = 0; cc < 5; ++cc) {
;             union { u32x4 u; bf16x8 v; } pf; pf.u.x = cvt_pk_bf16(s[2 * cc][0], s[2 * cc][1]); pf.u.y = cvt_pk_bf16(s[2 * cc][2], s[2 * cc][3]);
;             pf.u.z = cvt_pk_bf16(s[2 * cc + 1][0], s[2 * cc + 1][1]); pf.u.w = cvt_pk_bf16(s[2 * cc + 1][2], s[2 * cc + 1][3]);
; #pragma unroll
;             for (int et = 0; et < 4; ++et) { const bf16_t* vp = vbase + (cc * 32) * VSR + et * 16;
;                 const s16x4 v0 = __builtin_amdgcn_ds_read_tr16_b64_v4i16((LAS s16x4*)(LAS unsigned char*)vp), v1 = __builtin_amdgcn_ds_read_tr16_b64_v4i16((LAS s16x4*)(LAS unsigned char*)(vp + 16 * VSR));
;                 const bf16x8 vf = {v0[0], v0[1], v0[2], v0[3], v1[0], v1[1], v1[2], v1[3]};
;                 o[et] = __builtin_amdgcn_mfma_f32_16x16x32_bf16(vf, pf.v, o[et], 0, 0, 0); } }
.Latt_join:
	s_mov_b32 s35, 0xf149f2ca
	v_max3_f32 v48, v114, s35, v113
	v_max3_f32 v48, v48, v85, v84
	v_max3_f32 v48, v48, v87, v86
	v_max3_f32 v48, v48, v81, v80
	v_max3_f32 v48, v48, v83, v82
	v_max3_f32 v48, v48, v77, v76
	v_max3_f32 v48, v48, v79, v78
	v_max3_f32 v48, v48, v73, v72
	v_max3_f32 v48, v48, v75, v74
	v_max3_f32 v48, v48, v69, v68
	v_max3_f32 v48, v48, v71, v70
	v_max3_f32 v48, v48, v118, v117
	v_max3_f32 v48, v48, v65, v64
	v_max3_f32 v48, v48, v66, v60
	v_max3_f32 v48, v48, v62, v61
	v_max3_f32 v48, v48, v55, v54
	v_max3_f32 v48, v48, v56, v52
	v_and_b32_e32 v51, 64, v243
	v_max3_f32 v50, v48, v53, v49
	v_xor_b32_e32 v48, 16, v243
	v_add_u32_e32 v51, 64, v51
	v_cmp_lt_i32_e32 vcc, v48, v51
	s_mulk_i32 s34, 0x2aab
	s_lshr_b32 s35, s34, 31
	v_cndmask_b32_e32 v48, v243, v48, vcc
	v_lshlrev_b32_e32 v48, 2, v48
	v_mov_b32_e32 v57, v50
	s_ashr_i32 s34, s34, 22
	s_add_i32 s34, s34, s35
	s_sub_i32 s35, 5, s24
	s_bfe_i64 s[58:59], s[34:35], 0x100000
	v_permlane16_swap_b32 v57, v50
	s_nop 1
	v_max_f32_e32 v57, v57, v57
	v_max_f32_e32 v50, v50, v57
	v_xor_b32_e32 v57, 32, v243
	v_cmp_lt_i32_e32 vcc, v57, v51
	s_lshr_b32 s31, s31, s35
	s_lshl_b64 s[34:35], s[58:59], 11
	v_cndmask_b32_e32 v51, v243, v57, vcc
	v_lshlrev_b32_e32 v51, 2, v51
	v_mov_b32_e32 v57, v50
	s_or_b32 s34, s34, s31
	s_nop 1
	v_permlane32_swap_b32 v57, v50
	s_nop 1
	v_max_f32_e32 v57, v57, v57
	v_max_f32_e32 v50, v50, v57
	v_sub_f32_e32 v57, v114, v50
	v_exp_f32_e32 v57, v57
	v_sub_f32_e32 v58, v113, v50
	v_exp_f32_e32 v58, v58
	v_sub_f32_e32 v59, v85, v50
	v_exp_f32_e32 v59, v59
	v_sub_f32_e32 v63, v84, v50
	v_exp_f32_e32 v63, v63
	v_sub_f32_e32 v84, v87, v50
	v_add_f32_e32 v67, 0, v57
	v_exp_f32_e32 v84, v84
	v_sub_f32_e32 v85, v86, v50
	v_add_f32_e32 v67, v58, v67
	v_exp_f32_e32 v85, v85
	v_sub_f32_e32 v81, v81, v50
	v_add_f32_e32 v67, v59, v67
	v_exp_f32_e32 v81, v81
	v_sub_f32_e32 v80, v80, v50
	v_add_f32_e32 v67, v63, v67
	v_exp_f32_e32 v80, v80
	v_sub_f32_e32 v83, v83, v50
	v_add_f32_e32 v67, v84, v67
	v_exp_f32_e32 v113, v83
	v_sub_f32_e32 v82, v82, v50
	v_add_f32_e32 v67, v85, v67
	v_exp_f32_e32 v114, v82
	v_sub_f32_e32 v77, v77, v50
	v_add_f32_e32 v67, v81, v67
	v_exp_f32_e32 v115, v77
	v_sub_f32_e32 v76, v76, v50
	v_add_f32_e32 v67, v80, v67
	v_exp_f32_e32 v116, v76
	v_sub_f32_e32 v76, v79, v50
	v_add_f32_e32 v67, v113, v67
	v_exp_f32_e32 v119, v76
	v_sub_f32_e32 v76, v78, v50
	v_add_f32_e32 v67, v114, v67
	v_exp_f32_e32 v120, v76
	v_sub_f32_e32 v73, v73, v50
	v_add_f32_e32 v67, v115, v67
	v_exp_f32_e32 v121, v73
	v_sub_f32_e32 v72, v72, v50
	v_add_f32_e32 v67, v116, v67
	v_exp_f32_e32 v122, v72
	v_sub_f32_e32 v72, v75, v50
	v_add_f32_e32 v67, v119, v67
	v_exp_f32_e32 v126, v72
	v_sub_f32_e32 v72, v74, v50
	v_add_f32_e32 v67, v120, v67
	v_exp_f32_e32 v127, v72
	v_sub_f32_e32 v69, v69, v50
	v_add_f32_e32 v67, v121, v67
	v_exp_f32_e32 v128, v69
	v_sub_f32_e32 v68, v68, v50
	v_add_f32_e32 v67, v122, v67
	v_exp_f32_e32 v129, v68
	v_sub_f32_e32 v68, v71, v50
	v_add_f32_e32 v67, v126, v67
	v_exp_f32_e32 v130, v68
	v_sub_f32_e32 v68, v70, v50
	v_add_f32_e32 v67, v127, v67
	v_exp_f32_e32 v131, v68
	v_sub_f32_e32 v68, v118, v50
	v_add_f32_e32 v67, v128, v67
	v_exp_f32_e32 v132, v68
	v_sub_f32_e32 v68, v117, v50
	v_add_f32_e32 v67, v129, v67
	v_exp_f32_e32 v133, v68
	v_cvt_pk_bf16_f32 v68, v57, v58
	ds_read_b64_tr_b16 v[74:75], v111 offset:41472
	ds_read_b64_tr_b16 v[72:73], v111 offset:39168
	v_cvt_pk_bf16_f32 v70, v84, v85
	v_cvt_pk_bf16_f32 v71, v81, v80
	ds_read_b64_tr_b16 v[78:79], v111 offset:41504
	ds_read_b64_tr_b16 v[76:77], v111 offset:39200
	ds_read_b64_tr_b16 v[80:81], v111 offset:39232
	ds_read_b64_tr_b16 v[84:85], v111 offset:39264
	ds_read_b64_tr_b16 v[82:83], v111 offset:41536
	ds_read_b64_tr_b16 v[86:87], v111 offset:41568
	v_sub_f32_e32 v57, v65, v50
	v_add_f32_e32 v67, v130, v67
	v_exp_f32_e32 v134, v57
	v_add_f32_e32 v67, v131, v67
	v_add_f32_e32 v67, v132, v67
	v_sub_f32_e32 v57, v64, v50
	v_add_f32_e32 v117, v133, v67
	v_cvt_pk_bf16_f32 v69, v59, v63
	v_exp_f32_e32 v135, v57
	v_sub_f32_e32 v57, v66, v50
	s_waitcnt lgkmcnt(6)
	v_mfma_f32_16x16x32_bf16 v[72:75], v[72:75], v[68:71], 0
	v_exp_f32_e32 v136, v57
	v_add_f32_e32 v57, v134, v117
	v_sub_f32_e32 v58, v60, v50
	s_waitcnt lgkmcnt(4)
	v_mfma_f32_16x16x32_bf16 v[76:79], v[76:79], v[68:71], 0
	v_add_f32_e32 v57, v135, v57
	v_sub_f32_e32 v55, v55, v50
	v_add_f32_e32 v57, v136, v57
	s_waitcnt lgkmcnt(1)
	v_mfma_f32_16x16x32_bf16 v[64:67], v[80:83], v[68:71], 0
	v_cvt_pk_bf16_f32 v80, v113, v114
	v_cvt_pk_bf16_f32 v81, v115, v116
	v_cvt_pk_bf16_f32 v82, v119, v120
	s_waitcnt lgkmcnt(0)
	v_mfma_f32_16x16x32_bf16 v[68:71], v[84:87], v[68:71], 0
	ds_read_b64_tr_b16 v[84:85], v111 offset:43776
	ds_read_b64_tr_b16 v[86:87], v111 offset:46080
	v_cvt_pk_bf16_f32 v83, v121, v122
	ds_read_b64_tr_b16 v[116:117], v111 offset:46112
	ds_read_b64_tr_b16 v[114:115], v111 offset:43808
	ds_read_b64_tr_b16 v[118:119], v111 offset:43840
	ds_read_b64_tr_b16 v[122:123], v111 offset:43872
	ds_read_b64_tr_b16 v[120:121], v111 offset:46144
	ds_read_b64_tr_b16 v[124:125], v111 offset:46176
	v_exp_f32_e32 v113, v58
	v_sub_f32_e32 v58, v62, v50
	v_exp_f32_e32 v137, v58
	v_sub_f32_e32 v58, v61, v50
	s_waitcnt lgkmcnt(6)
	v_mfma_f32_16x16x32_bf16 v[72:75], v[84:87], v[80:83], v[72:75]
	v_exp_f32_e32 v138, v58
	v_sub_f32_e32 v54, v54, v50
	v_add_f32_e32 v57, v113, v57
	s_waitcnt lgkmcnt(4)
	v_mfma_f32_16x16x32_bf16 v[76:79], v[114:117], v[80:83], v[76:79]
	v_add_f32_e32 v57, v137, v57
	v_add_f32_e32 v139, v138, v57
	v_sub_f32_e32 v52, v52, v50
	s_waitcnt lgkmcnt(1)
; #define LAS __attribute__((address_space(3)))
; __device__ __forceinline__ unsigned cvt_pk_bf16(float lo, float hi) { const f32x2_t v = {lo, hi}; const bf16x2_t b = __builtin_convertvector(v, bf16x2_t); return __builtin_bit_cast(unsigned, b); }
; __device__ void attn_phase(unsigned char* smem, const Params& p, int chunk) {
;     ...
;         for (int cc = 0; cc < 5; ++cc) {
;             union { u32x4 u; bf16x8 v; } pf; pf.u.x = cvt_pk_bf16(s[2 * cc][0], s[2 * cc][1]); pf.u.y = cvt_pk_bf16(s[2 * cc][2], s[2 * cc][3]);
;             pf.u.z = cvt_pk_bf16(s[2 * cc + 1][0], s[2 * cc + 1][1]); pf.u.w = cvt_pk_bf16(s[2 * cc + 1][2], s[2 * cc + 1][3]);
; #pragma unroll
;             for (int et = 0; et < 4; ++et) { const bf16_t* vp = vbase + (cc * 32) * VSR + et * 16;
;                 const s16x4 v0 = __builtin_amdgcn_ds_read_tr16_b64_v4i16((LAS s16x4*)(LAS unsigned char*)vp), v1 = __builtin_amdgcn_ds_read_tr16_b64_v4i16((LAS s16x4*)(LAS unsigned char*)(vp + 16 * VSR));
;                 const bf16x8 vf = {v0[0], v0[1], v0[2], v0[3], v1[0], v1[1], v1[2], v1[3]};
;                 o[et] = __builtin_amdgcn_mfma_f32_16x16x32_bf16(vf, pf.v, o[et], 0, 0, 0); } }
;         const float inv = __builtin_amdgcn_rcpf(den);
;         bf16_t* op = qkv + qtok * QKVC + hh * 64 + 4 * g4;
; #pragma unroll
;         for (int et = 0; et < 4; ++et) { u32x2 wv; wv.x = cvt_pk_bf16(o[et][0] * inv, o[et][1] * inv); wv.y = cvt_pk_bf16(o[et][2] * inv, o[et][3] * inv); *(u32x2*)(op + et * 16) = wv; }
;         if (g4 == 0) lse[qtok * 24 + hh] = mx * 0.6931471805599453f + logf(den);
	v_mfma_f32_16x16x32_bf16 v[58:61], v[118:121], v[80:83], v[64:67]
	v_sub_f32_e32 v49, v49, v50
	v_exp_f32_e32 v49, v49
	s_waitcnt lgkmcnt(0)
	v_mfma_f32_16x16x32_bf16 v[62:65], v[122:125], v[80:83], v[68:71]
	ds_read_b64_tr_b16 v[80:81], v111 offset:48384
	ds_read_b64_tr_b16 v[82:83], v111 offset:50688
	v_cvt_pk_bf16_f32 v66, v126, v127
	v_cvt_pk_bf16_f32 v67, v128, v129
	v_cvt_pk_bf16_f32 v68, v130, v131
	v_cvt_pk_bf16_f32 v69, v132, v133
	ds_read_b64_tr_b16 v[86:87], v111 offset:50720
	ds_read_b64_tr_b16 v[84:85], v111 offset:48416
	ds_read_b64_tr_b16 v[114:115], v111 offset:48448
	ds_read_b64_tr_b16 v[118:119], v111 offset:48480
	ds_read_b64_tr_b16 v[116:117], v111 offset:50752
	ds_read_b64_tr_b16 v[120:121], v111 offset:50784
	s_waitcnt lgkmcnt(6)
	v_mfma_f32_16x16x32_bf16 v[70:73], v[80:83], v[66:69], v[72:75]
	v_exp_f32_e32 v80, v55
	s_waitcnt lgkmcnt(4)
	v_mfma_f32_16x16x32_bf16 v[74:77], v[84:87], v[66:69], v[76:79]
	s_nop 2
	v_exp_f32_e32 v78, v54
	v_sub_f32_e32 v54, v56, v50
	v_exp_f32_e32 v86, v54
	s_waitcnt lgkmcnt(1)
	v_mfma_f32_16x16x32_bf16 v[54:57], v[114:117], v[66:69], v[58:61]
	s_nop 2
	v_add_f32_e32 v58, v80, v139
	v_add_f32_e32 v58, v78, v58
	v_add_f32_e32 v87, v86, v58
	s_waitcnt lgkmcnt(0)
	v_mfma_f32_16x16x32_bf16 v[58:61], v[118:121], v[66:69], v[62:65]
	ds_read_b64_tr_b16 v[66:67], v111 offset:52992
	ds_read_b64_tr_b16 v[68:69], v111 offset:55296
	s_nop 0
	v_cvt_pk_bf16_f32 v62, v134, v135
	v_cvt_pk_bf16_f32 v63, v136, v113
	v_cvt_pk_bf16_f32 v64, v137, v138
	v_cvt_pk_bf16_f32 v65, v80, v78
	ds_read_b64_tr_b16 v[80:81], v111 offset:55328
	ds_read_b64_tr_b16 v[78:79], v111 offset:53024
	ds_read_b64_tr_b16 v[82:83], v111 offset:53056
	ds_read_b64_tr_b16 v[114:115], v111 offset:53088
	ds_read_b64_tr_b16 v[84:85], v111 offset:55360
	ds_read_b64_tr_b16 v[116:117], v111 offset:55392
	v_exp_f32_e32 v113, v52
	v_sub_f32_e32 v52, v53, v50
	s_waitcnt lgkmcnt(6)
	v_mfma_f32_16x16x32_bf16 v[66:69], v[66:69], v[62:65], v[70:73]
	s_waitcnt lgkmcnt(4)
	v_mfma_f32_16x16x32_bf16 v[70:73], v[78:81], v[62:65], v[74:77]
	s_nop 2
	v_exp_f32_e32 v74, v52
	s_waitcnt lgkmcnt(1)
	v_mfma_f32_16x16x32_bf16 v[52:55], v[82:85], v[62:65], v[54:57]
	s_nop 2
	v_add_f32_e32 v56, v113, v87
	v_add_f32_e32 v56, v74, v56
	v_add_f32_e32 v87, v49, v56
	s_waitcnt lgkmcnt(0)
	v_mfma_f32_16x16x32_bf16 v[56:59], v[114:117], v[62:65], v[58:61]
	v_mov_b32_e32 v62, v185
	v_mov_b32_e32 v63, v185
	s_nop 0
	v_cvt_pk_bf16_f32 v61, v74, v49
	ds_read_b64_tr_b16 v[74:75], v111 offset:57600
	ds_read_b64_tr_b16 v[76:77], v111 offset:59904
	ds_bpermute_b32 v49, v48, v87
	v_cvt_pk_bf16_f32 v60, v86, v113
	ds_read_b64_tr_b16 v[80:81], v111 offset:59936
	ds_read_b64_tr_b16 v[78:79], v111 offset:57632
	ds_read_b64_tr_b16 v[82:83], v111 offset:57664
	ds_read_b64_tr_b16 v[114:115], v111 offset:57696
	ds_read_b64_tr_b16 v[84:85], v111 offset:59968
	ds_read_b64_tr_b16 v[116:117], v111 offset:60000
	s_waitcnt lgkmcnt(7)
	v_mfma_f32_16x16x32_bf16 v[64:67], v[74:77], v[60:63], v[66:69]
	v_lshl_or_b32 v48, v101, 6, v106
	v_mov_b32_e32 v101, v185
	s_waitcnt lgkmcnt(4)
	v_mfma_f32_16x16x32_bf16 v[68:71], v[78:81], v[60:63], v[70:73]
	s_nop 2
	v_add_f32_e32 v72, v87, v49
	ds_bpermute_b32 v51, v51, v72
	v_ashrrev_i32_e32 v49, 31, v48
	v_lshlrev_b64 v[48:49], s24, v[48:49]
	s_waitcnt lgkmcnt(2)
	v_mfma_f32_16x16x32_bf16 v[52:55], v[82:85], v[60:63], v[52:55]
	v_lshl_add_u64 v[48:49], s[34:35], 0, v[48:49]
	s_waitcnt lgkmcnt(0)
	v_add_f32_e32 v51, v72, v51
	v_mfma_f32_16x16x32_bf16 v[56:59], v[114:117], v[60:63], v[56:59]
	v_mov_b64_e32 v[62:63], s[6:7]
	v_mad_u64_u32 v[62:63], s[34:35], v48, s93, v[62:63]
	v_rcp_f32_e32 v60, v51
	v_mov_b32_e32 v72, v63
	v_mad_u64_u32 v[72:73], s[34:35], v49, s93, v[72:73]
	s_lshl_b32 s34, s52, 6
	v_mov_b32_e32 v63, v72
	s_ashr_i32 s35, s34, 31
	v_lshl_add_u64 v[62:63], s[34:35], 1, v[62:63]
	v_pk_mul_f32 v[64:65], v[60:61], v[64:65] op_sel_hi:[0,1]
	v_pk_mul_f32 v[66:67], v[60:61], v[66:67] op_sel_hi:[0,1]
	v_pk_mul_f32 v[52:53], v[60:61], v[52:53] op_sel_hi:[0,1]
	v_pk_mul_f32 v[54:55], v[60:61], v[54:55] op_sel_hi:[0,1]
	v_lshl_add_u64 v[62:63], v[62:63], 0, v[100:101]
	v_cvt_pk_bf16_f32 v64, v64, v65
	v_cvt_pk_bf16_f32 v65, v66, v67
	v_cvt_pk_bf16_f32 v52, v52, v53
	v_cvt_pk_bf16_f32 v53, v54, v55
	global_store_dwordx2 v[62:63], v[64:65], off
	v_pk_mul_f32 v[64:65], v[60:61], v[68:69] op_sel_hi:[0,1]
	v_pk_mul_f32 v[66:67], v[60:61], v[70:71] op_sel_hi:[0,1]
	global_store_dwordx2 v[62:63], v[52:53], off offset:64
	v_pk_mul_f32 v[52:53], v[60:61], v[56:57] op_sel_hi:[0,1]
	v_pk_mul_f32 v[54:55], v[60:61], v[58:59] op_sel_hi:[0,1]
	v_cvt_pk_bf16_f32 v64, v64, v65
	v_cvt_pk_bf16_f32 v65, v66, v67
	v_cvt_pk_bf16_f32 v52, v52, v53
	v_cvt_pk_bf16_f32 v53, v54, v55
	global_store_dwordx2 v[62:63], v[64:65], off offset:32
	global_store_dwordx2 v[62:63], v[52:53], off offset:96
	s_and_saveexec_b64 s[58:59], s[10:11]
	s_cbranch_execz .LBB0_49
	s_mov_b32 s24, 0x800000
	v_cmp_gt_f32_e32 vcc, s24, v51
	s_mov_b32 s24, 0x3f317217
	s_ashr_i32 s53, s52, 31
	v_cndmask_b32_e64 v52, 0, 32, vcc
	v_ldexp_f32 v51, v51, v52
	v_log_f32_e32 v51, v51
	v_cndmask_b32_e32 v52, 0, v140, vcc
	v_mul_f32_e32 v53, 0x3f317217, v51
	v_fma_f32 v53, v51, s24, -v53
	v_fmac_f32_e32 v53, 0x3377d1cf, v51
	v_fmac_f32_e32 v53, 0x3f317217, v51
	v_cmp_lt_f32_e64 vcc, |v51|, s70
	s_nop 1
	v_cndmask_b32_e32 v51, v51, v53, vcc
	v_sub_f32_e32 v52, v51, v52
	v_fmac_f32_e32 v52, 0x3f317218, v50
	v_mov_b64_e32 v[50:51], s[0:1]
	v_mad_u64_u32 v[50:51], s[34:35], v48, s92, v[50:51]
	v_mov_b32_e32 v48, v51
	v_mad_u64_u32 v[48:49], s[34:35], v49, s92, v[48:49]
	v_mov_b32_e32 v51, v48
	v_lshl_add_u64 v[48:49], s[52:53], 2, v[50:51]
	global_store_dword v[48:49], v52, off
	s_branch .LBB0_49
